# GEMM second half-steps: prefetch fragment reads spread one per MFMA through the first MFMA group instead of a burst between the groups
# speedup vs baseline: 1.0423x; 1.0021x over previous
.LBB0_127:
	s_waitcnt lgkmcnt(0)
	s_barrier
	s_add_i32 s26, s8, -2
	s_and_b32 s28, s26, 3
	s_mulk_i32 s28, 0x6000
	v_add_u32_e32 v127, s28, v140
	v_add_u32_e32 v143, s28, v141
	ds_read_b128 v[26:29], v143
	v_mfma_f32_16x16x32_bf16 v[74:77], v[2:5], v[106:109], v[74:77]
	ds_read_b128 v[22:25], v143 offset:1024
	v_mfma_f32_16x16x32_bf16 v[58:61], v[6:9], v[106:109], v[58:61]
	ds_read_b128 v[118:121], v127
	v_mfma_f32_16x16x32_bf16 v[38:41], v[10:13], v[106:109], v[38:41]
	ds_read_b128 v[114:117], v127 offset:1024
	v_mfma_f32_16x16x32_bf16 v[30:33], v[14:17], v[106:109], v[30:33]
	ds_read_b128 v[110:113], v127 offset:2048
	ds_read_b128 v[106:109], v127 offset:3072
	v_mfma_f32_16x16x32_bf16 v[94:97], v[2:5], v[144:147], v[94:97]
	v_mfma_f32_16x16x32_bf16 v[82:85], v[6:9], v[144:147], v[82:85]
	v_mfma_f32_16x16x32_bf16 v[66:69], v[10:13], v[144:147], v[66:69]
	v_mfma_f32_16x16x32_bf16 v[34:37], v[14:17], v[144:147], v[34:37]
	s_mov_b64 s[26:27], -1
	s_and_b64 vcc, exec, s[24:25]
	s_cbranch_vccz .LBB0_129
	s_waitcnt vmcnt(0)
	s_mov_b64 s[26:27], 0

.LBB0_133:
	s_waitcnt lgkmcnt(0)
	s_barrier
	s_andn2_b64 vcc, exec, s[22:23]
	s_cbranch_vccnz .Lgm_G5x_noread
	s_add_i32 s19, s8, -1
	s_and_b32 s19, s19, 2
	s_mulk_i32 s19, 0x6000
	v_add_u32_e32 v127, s19, v140
	v_add_u32_e32 v132, s19, v141
	ds_read_b128 v[26:29], v132
	v_mfma_f32_16x16x32_bf16 v[74:77], v[118:121], v[144:147], v[74:77]
	ds_read_b128 v[22:25], v132 offset:1024
	v_mfma_f32_16x16x32_bf16 v[58:61], v[114:117], v[144:147], v[58:61]
	ds_read_b128 v[2:5], v127
	v_mfma_f32_16x16x32_bf16 v[38:41], v[110:113], v[144:147], v[38:41]
	ds_read_b128 v[6:9], v127 offset:1024
	v_mfma_f32_16x16x32_bf16 v[30:33], v[106:109], v[144:147], v[30:33]
	ds_read_b128 v[10:13], v127 offset:2048
	ds_read_b128 v[14:17], v127 offset:3072
	s_branch .LBB0_120

.Lgm_G5x_noread:
	v_mfma_f32_16x16x32_bf16 v[74:77], v[118:121], v[144:147], v[74:77]
	v_mfma_f32_16x16x32_bf16 v[58:61], v[114:117], v[144:147], v[58:61]
	v_mfma_f32_16x16x32_bf16 v[38:41], v[110:113], v[144:147], v[38:41]
	v_mfma_f32_16x16x32_bf16 v[30:33], v[106:109], v[144:147], v[30:33]
	s_branch .LBB0_120

.LBB0_189:
	s_waitcnt lgkmcnt(0)
	s_barrier
	s_add_i32 s28, s31, 0xffff0000
	s_and_b32 s35, s28, 0x18000
	v_add_u32_e32 v187, s35, v200
	v_add_u32_e32 v226, s35, v201
	ds_read_b128 v[150:153], v226
	v_mfma_f32_16x16x32_bf16 v[154:157], v[122:125], v[162:165], v[154:157]
	ds_read_b128 v[146:149], v226 offset:1024
	v_mfma_f32_16x16x32_bf16 v[90:93], v[126:129], v[162:165], v[90:93]
	ds_read_b128 v[142:145], v226 offset:2048
	v_mfma_f32_16x16x32_bf16 v[58:61], v[130:133], v[162:165], v[58:61]
	ds_read_b128 v[138:141], v226 offset:3072
	v_mfma_f32_16x16x32_bf16 v[26:29], v[134:137], v[162:165], v[26:29]
	ds_read_b128 v[174:177], v187
	v_mfma_f32_16x16x32_bf16 v[114:117], v[122:125], v[166:169], v[114:117]
	ds_read_b128 v[170:173], v187 offset:1024
	v_mfma_f32_16x16x32_bf16 v[82:85], v[126:129], v[166:169], v[82:85]
	ds_read_b128 v[162:165], v187 offset:3072
	v_mfma_f32_16x16x32_bf16 v[50:53], v[130:133], v[166:169], v[50:53]
	v_mfma_f32_16x16x32_bf16 v[18:21], v[134:137], v[166:169], v[18:21]
	ds_read_b128 v[166:169], v187 offset:2048
	v_mfma_f32_16x16x32_bf16 v[106:109], v[122:125], v[232:235], v[106:109]
	v_mfma_f32_16x16x32_bf16 v[74:77], v[126:129], v[232:235], v[74:77]
	v_mfma_f32_16x16x32_bf16 v[42:45], v[130:133], v[232:235], v[42:45]
	v_mfma_f32_16x16x32_bf16 v[10:13], v[134:137], v[232:235], v[10:13]
	v_mfma_f32_16x16x32_bf16 v[98:101], v[122:125], v[236:239], v[98:101]
	v_mfma_f32_16x16x32_bf16 v[66:69], v[126:129], v[236:239], v[66:69]
	v_mfma_f32_16x16x32_bf16 v[34:37], v[130:133], v[236:239], v[34:37]
	v_mfma_f32_16x16x32_bf16 v[2:5], v[134:137], v[236:239], v[2:5]
	s_mov_b64 s[28:29], -1
	s_and_b64 vcc, exec, s[26:27]
	s_cbranch_vccz .LBB0_191
	s_waitcnt vmcnt(0)
	s_mov_b64 s[28:29], 0

.LBB0_195:
	s_waitcnt lgkmcnt(0)
	s_barrier
	s_andn2_b64 vcc, exec, s[24:25]
	s_cbranch_vccnz .Lgm_G4x_noread
	s_add_i32 s24, s31, 0xffff8000
	s_and_b32 s24, s24, 0x10000
	v_add_u32_e32 v187, s24, v200
	v_add_u32_e32 v226, s24, v201
	ds_read_b128 v[150:153], v226
	v_mfma_f32_16x16x32_bf16 v[154:157], v[174:177], v[232:235], v[154:157]
	ds_read_b128 v[146:149], v226 offset:1024
	v_mfma_f32_16x16x32_bf16 v[90:93], v[170:173], v[232:235], v[90:93]
	ds_read_b128 v[142:145], v226 offset:2048
	v_mfma_f32_16x16x32_bf16 v[58:61], v[166:169], v[232:235], v[58:61]
	ds_read_b128 v[138:141], v226 offset:3072
	v_mfma_f32_16x16x32_bf16 v[26:29], v[162:165], v[232:235], v[26:29]
	ds_read_b128 v[122:125], v187
	v_mfma_f32_16x16x32_bf16 v[114:117], v[174:177], v[236:239], v[114:117]
	ds_read_b128 v[126:129], v187 offset:1024
	v_mfma_f32_16x16x32_bf16 v[82:85], v[170:173], v[236:239], v[82:85]
	ds_read_b128 v[130:133], v187 offset:2048
	v_mfma_f32_16x16x32_bf16 v[50:53], v[166:169], v[236:239], v[50:53]
	ds_read_b128 v[134:137], v187 offset:3072
	v_mfma_f32_16x16x32_bf16 v[18:21], v[162:165], v[236:239], v[18:21]
	s_branch .LBB0_182

.Lgm_G4x_noread:
	v_mfma_f32_16x16x32_bf16 v[154:157], v[174:177], v[232:235], v[154:157]
	v_mfma_f32_16x16x32_bf16 v[90:93], v[170:173], v[232:235], v[90:93]
	v_mfma_f32_16x16x32_bf16 v[58:61], v[166:169], v[232:235], v[58:61]
	v_mfma_f32_16x16x32_bf16 v[26:29], v[162:165], v[232:235], v[26:29]
	v_mfma_f32_16x16x32_bf16 v[114:117], v[174:177], v[236:239], v[114:117]
	v_mfma_f32_16x16x32_bf16 v[82:85], v[170:173], v[236:239], v[82:85]
	v_mfma_f32_16x16x32_bf16 v[50:53], v[166:169], v[236:239], v[50:53]
	v_mfma_f32_16x16x32_bf16 v[18:21], v[162:165], v[236:239], v[18:21]
	s_branch .LBB0_182

.LBB0_415:
	s_waitcnt lgkmcnt(0)
	s_barrier
	s_add_i32 s19, s8, -2
	s_and_b32 s29, s19, 3
	s_mulk_i32 s29, 0x6000
	v_add_u32_e32 v127, s29, v235
	v_add_u32_e32 v226, s29, v236
	ds_read_b128 v[26:29], v226
	v_mfma_f32_16x16x32_bf16 v[90:93], v[14:17], v[106:109], v[90:93]
	ds_read_b128 v[18:21], v226 offset:1024
	v_mfma_f32_16x16x32_bf16 v[74:77], v[10:13], v[106:109], v[74:77]
	ds_read_b128 v[118:121], v127
	v_mfma_f32_16x16x32_bf16 v[58:61], v[6:9], v[106:109], v[58:61]
	ds_read_b128 v[114:117], v127 offset:1024
	v_mfma_f32_16x16x32_bf16 v[46:49], v[2:5], v[106:109], v[46:49]
	ds_read_b128 v[110:113], v127 offset:2048
	ds_read_b128 v[106:109], v127 offset:3072
	v_mfma_f32_16x16x32_bf16 v[94:97], v[14:17], v[242:245], v[94:97]
	v_mfma_f32_16x16x32_bf16 v[78:81], v[10:13], v[242:245], v[78:81]
	v_mfma_f32_16x16x32_bf16 v[62:65], v[6:9], v[242:245], v[62:65]
	v_mfma_f32_16x16x32_bf16 v[42:45], v[2:5], v[242:245], v[42:45]
	s_mov_b64 s[26:27], -1
	s_and_b64 vcc, exec, s[24:25]
	s_cbranch_vccz .LBB0_417
	s_waitcnt vmcnt(0)
	s_mov_b64 s[26:27], 0

.LBB0_651:
	s_waitcnt lgkmcnt(0)
	s_barrier
	s_add_i32 s28, s31, 0xffff0000
	s_and_b32 s35, s28, 0x18000
	v_add_u32_e32 v189, s35, v231
	v_add_u32_e32 v226, s35, v232
	ds_read_b128 v[158:161], v226
	v_mfma_f32_16x16x32_bf16 v[110:113], v[130:133], v[162:165], v[110:113]
	ds_read_b128 v[154:157], v226 offset:1024
	v_mfma_f32_16x16x32_bf16 v[78:81], v[134:137], v[162:165], v[78:81]
	ds_read_b128 v[150:153], v226 offset:2048
	v_mfma_f32_16x16x32_bf16 v[46:49], v[138:141], v[162:165], v[46:49]
	ds_read_b128 v[146:149], v226 offset:3072
	v_mfma_f32_16x16x32_bf16 v[14:17], v[142:145], v[162:165], v[14:17]
	ds_read_b128 v[174:177], v189
	v_mfma_f32_16x16x32_bf16 v[106:109], v[130:133], v[166:169], v[106:109]
	ds_read_b128 v[170:173], v189 offset:1024
	v_mfma_f32_16x16x32_bf16 v[74:77], v[134:137], v[166:169], v[74:77]
	ds_read_b128 v[162:165], v189 offset:3072
	v_mfma_f32_16x16x32_bf16 v[42:45], v[138:141], v[166:169], v[42:45]
	v_mfma_f32_16x16x32_bf16 v[10:13], v[142:145], v[166:169], v[10:13]
	ds_read_b128 v[166:169], v189 offset:2048
	v_mfma_f32_16x16x32_bf16 v[102:105], v[130:133], v[234:237], v[102:105]
	v_mfma_f32_16x16x32_bf16 v[70:73], v[134:137], v[234:237], v[70:73]
	v_mfma_f32_16x16x32_bf16 v[38:41], v[138:141], v[234:237], v[38:41]
	v_mfma_f32_16x16x32_bf16 v[6:9], v[142:145], v[234:237], v[6:9]
	v_mfma_f32_16x16x32_bf16 v[94:97], v[130:133], v[238:241], v[94:97]
	v_mfma_f32_16x16x32_bf16 v[62:65], v[134:137], v[238:241], v[62:65]
	v_mfma_f32_16x16x32_bf16 v[30:33], v[138:141], v[238:241], v[30:33]
	v_mfma_f32_16x16x32_bf16 v[2:5], v[142:145], v[238:241], v[2:5]
	s_mov_b64 s[28:29], -1
	s_and_b64 vcc, exec, s[26:27]
	s_cbranch_vccz .LBB0_653
	s_waitcnt vmcnt(0)
	s_mov_b64 s[28:29], 0

.LBB0_657:
	s_waitcnt lgkmcnt(0)
	s_barrier
	s_andn2_b64 vcc, exec, s[24:25]
	s_cbranch_vccnz .Lgm_G1x_noread
	s_add_i32 s24, s31, 0xffff8000
	s_and_b32 s24, s24, 0x10000
	v_add_u32_e32 v189, s24, v231
	v_add_u32_e32 v226, s24, v232
	ds_read_b128 v[158:161], v226
	v_mfma_f32_16x16x32_bf16 v[110:113], v[174:177], v[234:237], v[110:113]
	ds_read_b128 v[154:157], v226 offset:1024
	v_mfma_f32_16x16x32_bf16 v[78:81], v[170:173], v[234:237], v[78:81]
	ds_read_b128 v[150:153], v226 offset:2048
	v_mfma_f32_16x16x32_bf16 v[46:49], v[166:169], v[234:237], v[46:49]
	ds_read_b128 v[146:149], v226 offset:3072
	v_mfma_f32_16x16x32_bf16 v[14:17], v[162:165], v[234:237], v[14:17]
	ds_read_b128 v[130:133], v189
	v_mfma_f32_16x16x32_bf16 v[106:109], v[174:177], v[238:241], v[106:109]
	ds_read_b128 v[134:137], v189 offset:1024
	v_mfma_f32_16x16x32_bf16 v[74:77], v[170:173], v[238:241], v[74:77]
	ds_read_b128 v[138:141], v189 offset:2048
	v_mfma_f32_16x16x32_bf16 v[42:45], v[166:169], v[238:241], v[42:45]
	ds_read_b128 v[142:145], v189 offset:3072
	v_mfma_f32_16x16x32_bf16 v[10:13], v[162:165], v[238:241], v[10:13]
	s_branch .LBB0_644

.Lgm_G1x_noread:
	v_mfma_f32_16x16x32_bf16 v[110:113], v[174:177], v[234:237], v[110:113]
	v_mfma_f32_16x16x32_bf16 v[78:81], v[170:173], v[234:237], v[78:81]
	v_mfma_f32_16x16x32_bf16 v[46:49], v[166:169], v[234:237], v[46:49]
	v_mfma_f32_16x16x32_bf16 v[14:17], v[162:165], v[234:237], v[14:17]
	v_mfma_f32_16x16x32_bf16 v[106:109], v[174:177], v[238:241], v[106:109]
	v_mfma_f32_16x16x32_bf16 v[74:77], v[170:173], v[238:241], v[74:77]
	v_mfma_f32_16x16x32_bf16 v[42:45], v[166:169], v[238:241], v[42:45]
	v_mfma_f32_16x16x32_bf16 v[10:13], v[162:165], v[238:241], v[10:13]
	s_branch .LBB0_644
